# FFN1 and gate epilogue stores widened: v_permlane16_swap pairs two row groups so each lane issues one dwordx4 instead of two dwordx2 (same bytes, same addresses)
# baseline (speedup 1.0000x reference)
.LBB0_1578:
	v_mbcnt_lo_u32_b32 v251, -1, 0
	v_mbcnt_hi_u32_b32 v251, -1, v251
	v_bfe_u32 v251, v251, 4, 1
	v_mul_u32_u24_e32 v250, 0xbff8, v251
	v_mov_b32_e32 v251, 0
	v_lshl_or_b32 v164, s19, 8, v194
	v_ashrrev_i32_e32 v165, 31, v164
	v_lshl_add_u64 v[28:29], v[164:165], 2, s[16:17]
	global_load_dwordx4 v[40:43], v[28:29], off offset:16
	global_load_dwordx4 v[44:47], v[28:29], off
	global_load_dwordx4 v[24:27], v[28:29], off offset:528
	s_nop 0
	global_load_dwordx4 v[28:31], v[28:29], off offset:512
	v_lshl_add_u32 v166, s18, 8, v192
	v_ashrrev_i32_e32 v167, 31, v166
	v_readlane_b32 s26, v254, 8
	v_lshlrev_b64 v[196:197], 6, v[166:167]
	v_readlane_b32 s27, v254, 9
	s_mov_b32 s29, 0x800000
	s_mov_b32 s36, 0x437f0000
	v_lshl_add_u64 v[208:209], s[26:27], 0, v[196:197]
	v_mbcnt_lo_u32_b32 v198, -1, 0
	v_mbcnt_hi_u32_b32 v198, -1, v198
	v_and_b32_e32 v199, 48, v198
	v_xor_b32_e32 v210, 16, v198
	v_xor_b32_e32 v211, 32, v198
	v_lshlrev_b32_e32 v210, 2, v210
	v_lshlrev_b32_e32 v211, 2, v211
	v_mov_b32_e32 v198, v166
	v_lshl_or_b32 v198, v198, 6, v199
	global_load_dwordx4 v[200:203], v198, s[26:27]
	v_add_u32_e32 v198, 16, v166
	v_lshl_or_b32 v198, v198, 6, v199
	global_load_dwordx4 v[204:207], v198, s[26:27]
	v_add_u32_e32 v198, 32, v166
	v_lshl_or_b32 v198, v198, 6, v199
	global_load_dwordx4 v[212:215], v198, s[26:27]
	v_add_u32_e32 v198, 48, v166
	v_lshl_or_b32 v198, v198, 6, v199
	global_load_dwordx4 v[216:219], v198, s[26:27]
	v_add_u32_e32 v198, 128, v166
	v_lshl_or_b32 v198, v198, 6, v199
	global_load_dwordx4 v[220:223], v198, s[26:27]
	v_add_u32_e32 v198, 144, v166
	v_lshl_or_b32 v198, v198, 6, v199
	global_load_dwordx4 v[224:227], v198, s[26:27]
	v_add_u32_e32 v198, 160, v166
	v_lshl_or_b32 v198, v198, 6, v199
	global_load_dwordx4 v[228:231], v198, s[26:27]
	v_add_u32_e32 v198, 176, v166
	v_lshl_or_b32 v198, v198, 6, v199
	global_load_dwordx4 v[232:235], v198, s[26:27]
	s_waitcnt vmcnt(0)
	v_pk_add_f32 v[200:201], v[200:201], v[202:203]
	v_pk_add_f32 v[204:205], v[204:205], v[206:207]
	v_pk_add_f32 v[212:213], v[212:213], v[214:215]
	v_pk_add_f32 v[216:217], v[216:217], v[218:219]
	v_pk_add_f32 v[220:221], v[220:221], v[222:223]
	v_pk_add_f32 v[224:225], v[224:225], v[226:227]
	v_pk_add_f32 v[228:229], v[228:229], v[230:231]
	v_pk_add_f32 v[232:233], v[232:233], v[234:235]
	v_add_f32_e32 v200, v200, v201
	v_add_f32_e32 v204, v204, v205
	v_add_f32_e32 v212, v212, v213
	v_add_f32_e32 v216, v216, v217
	v_add_f32_e32 v220, v220, v221
	v_add_f32_e32 v224, v224, v225
	v_add_f32_e32 v228, v228, v229
	v_add_f32_e32 v232, v232, v233
	ds_bpermute_b32 v201, v210, v200
	ds_bpermute_b32 v205, v210, v204
	ds_bpermute_b32 v213, v210, v212
	ds_bpermute_b32 v217, v210, v216
	ds_bpermute_b32 v221, v210, v220
	ds_bpermute_b32 v225, v210, v224
	ds_bpermute_b32 v229, v210, v228
	ds_bpermute_b32 v233, v210, v232
	s_waitcnt lgkmcnt(0)
	v_add_f32_e32 v200, v200, v201
	v_add_f32_e32 v204, v204, v205
	v_add_f32_e32 v212, v212, v213
	v_add_f32_e32 v216, v216, v217
	v_add_f32_e32 v220, v220, v221
	v_add_f32_e32 v224, v224, v225
	v_add_f32_e32 v228, v228, v229
	v_add_f32_e32 v232, v232, v233
	ds_bpermute_b32 v201, v211, v200
	ds_bpermute_b32 v205, v211, v204
	ds_bpermute_b32 v213, v211, v212
	ds_bpermute_b32 v217, v211, v216
	ds_bpermute_b32 v221, v211, v220
	ds_bpermute_b32 v225, v211, v224
	ds_bpermute_b32 v229, v211, v228
	ds_bpermute_b32 v233, v211, v232
	s_waitcnt lgkmcnt(0)
	v_add_f32_e32 v200, v200, v201
	v_add_f32_e32 v204, v204, v205
	v_add_f32_e32 v212, v212, v213
	v_add_f32_e32 v216, v216, v217
	v_add_f32_e32 v220, v220, v221
	v_add_f32_e32 v224, v224, v225
	v_add_f32_e32 v228, v228, v229
	v_add_f32_e32 v232, v232, v233
	v_fmamk_f32 v200, v200, 0x3a800000, v171
	v_fmamk_f32 v204, v204, 0x3a800000, v171
	v_fmamk_f32 v212, v212, 0x3a800000, v171
	v_fmamk_f32 v216, v216, 0x3a800000, v171
	v_fmamk_f32 v220, v220, 0x3a800000, v171
	v_fmamk_f32 v224, v224, 0x3a800000, v171
	v_fmamk_f32 v228, v228, 0x3a800000, v171
	v_fmamk_f32 v232, v232, 0x3a800000, v171
	v_rsq_f32_e32 v203, v200
	v_rsq_f32_e32 v207, v204
	v_rsq_f32_e32 v215, v212
	v_rsq_f32_e32 v219, v216
	v_rsq_f32_e32 v223, v220
	v_rsq_f32_e32 v227, v224
	v_rsq_f32_e32 v231, v228
	v_rsq_f32_e32 v235, v232
	s_nop 0
	s_movk_i32 s28, 0xc00
	s_nop 0
	s_nop 0
	s_nop 0
	s_nop 0
	v_mov_b32_e32 v167, v203
	v_fma_f32 v136, v136, v167, v40
	v_mul_f32_e32 v136, 0xbfb8aa3b, v136
	v_fma_f32 v140, v140, v167, v44
	v_exp_f32_e32 v136, v136
	v_mul_f32_e32 v140, 0xbfb8aa3b, v140
	v_fma_f32 v138, v138, v167, v42
	v_exp_f32_e32 v140, v140
	v_mul_f32_e32 v138, 0xbfb8aa3b, v138
	v_exp_f32_e32 v138, v138
	v_add_f32_e32 v136, 1.0, v136
	v_rcp_f32_e32 v197, v136
	v_fma_f32 v136, v141, v167, v45
	v_fma_f32 v137, v137, v167, v41
	v_add_f32_e32 v140, 1.0, v140
	v_mul_f32_e32 v136, 0xbfb8aa3b, v136
	v_mul_f32_e32 v137, 0xbfb8aa3b, v137
	v_rcp_f32_e32 v196, v140
	v_exp_f32_e32 v136, v136
	v_exp_f32_e32 v137, v137
	v_fma_f32 v140, v142, v167, v46
	v_add_f32_e32 v138, 1.0, v138
	v_mul_f32_e32 v140, 0xbfb8aa3b, v140
	v_rcp_f32_e32 v141, v138
	v_fma_f32 v138, v143, v167, v47
	v_fma_f32 v139, v139, v167, v43
	v_exp_f32_e32 v140, v140
	v_mul_f32_e32 v138, 0xbfb8aa3b, v138
	v_mul_f32_e32 v139, 0xbfb8aa3b, v139
	v_exp_f32_e32 v138, v138
	v_exp_f32_e32 v139, v139
	v_add_f32_e32 v136, 1.0, v136
	v_add_f32_e32 v137, 1.0, v137
	v_rcp_f32_e32 v136, v136
	v_rcp_f32_e32 v137, v137
	v_add_f32_e32 v140, 1.0, v140
	v_rcp_f32_e32 v140, v140
	v_add_f32_e32 v138, 1.0, v138
	v_add_f32_e32 v139, 1.0, v139
	v_rcp_f32_e32 v138, v138
	v_rcp_f32_e32 v139, v139
	v_pk_fma_f32 v[136:137], v[136:137], s[36:37], 0.5 op_sel_hi:[1,0,0]
	v_pk_fma_f32 v[142:143], v[196:197], s[36:37], 0.5 op_sel_hi:[1,0,0]
	v_cvt_u32_f32_e32 v188, v136
	v_cvt_u32_f32_e32 v189, v137
	v_cvt_u32_f32_e32 v143, v143
	v_cvt_u32_f32_e32 v142, v142
	v_pk_fma_f32 v[136:137], v[140:141], s[36:37], 0.5 op_sel_hi:[1,0,0]
	v_fma_f32 v128, v128, v167, v24
	v_cvt_u32_f32_sdwa v140, v136 dst_sel:WORD_1 dst_unused:UNUSED_PAD src0_sel:DWORD
	v_cvt_u32_f32_sdwa v141, v137 dst_sel:WORD_1 dst_unused:UNUSED_PAD src0_sel:DWORD
	v_pk_fma_f32 v[136:137], v[138:139], s[36:37], 0.5 op_sel_hi:[1,0,0]
	v_lshlrev_b32_e32 v138, 8, v189
	v_cvt_u32_f32_sdwa v136, v136 dst_sel:BYTE_3 dst_unused:UNUSED_PAD src0_sel:DWORD
	v_cvt_u32_f32_sdwa v137, v137 dst_sel:BYTE_3 dst_unused:UNUSED_PAD src0_sel:DWORD
	v_lshlrev_b32_e32 v139, 8, v188
	v_mul_f32_e32 v128, 0xbfb8aa3b, v128
	v_or_b32_e32 v138, v138, v143
	v_or_b32_e32 v139, v139, v142
	v_fma_f32 v132, v132, v167, v28
	v_exp_f32_e32 v128, v128
	v_or_b32_e32 v138, v138, v141
	v_or_b32_e32 v139, v139, v140
	v_mul_f32_e32 v132, 0xbfb8aa3b, v132
	v_fma_f32 v130, v130, v167, v26
	v_or_b32_e32 v141, v138, v137
	v_or_b32_e32 v140, v139, v136
	v_mov_b64_e32 v[136:137], s[14:15]
	v_exp_f32_e32 v132, v132
	v_mul_f32_e32 v130, 0xbfb8aa3b, v130
	v_mad_i64_i32 v[138:139], s[18:19], v166, s28, v[136:137]
	v_exp_f32_e32 v130, v130
	v_lshl_add_u64 v[138:139], v[138:139], 0, v[164:165]
	v_add_f32_e32 v128, 1.0, v128
	v_lshl_add_u64 v[248:249], v[138:139], 0, v[250:251]
	v_mov_b64_e32 v[240:241], v[140:141]
	v_rcp_f32_e32 v141, v128
	v_fma_f32 v128, v133, v167, v29
	v_fma_f32 v129, v129, v167, v25
	v_add_f32_e32 v132, 1.0, v132
	v_mul_f32_e32 v128, 0xbfb8aa3b, v128
	v_mul_f32_e32 v129, 0xbfb8aa3b, v129
	v_rcp_f32_e32 v140, v132
	v_exp_f32_e32 v128, v128
	v_exp_f32_e32 v129, v129
	v_fma_f32 v132, v134, v167, v30
	v_add_f32_e32 v130, 1.0, v130
	v_mul_f32_e32 v132, 0xbfb8aa3b, v132
	v_rcp_f32_e32 v133, v130
	v_fma_f32 v130, v135, v167, v31
	v_fma_f32 v131, v131, v167, v27
	v_exp_f32_e32 v132, v132
	v_mul_f32_e32 v130, 0xbfb8aa3b, v130
	v_mul_f32_e32 v131, 0xbfb8aa3b, v131
	v_exp_f32_e32 v130, v130
	v_exp_f32_e32 v131, v131
	v_add_f32_e32 v128, 1.0, v128
	v_add_f32_e32 v129, 1.0, v129
	v_rcp_f32_e32 v128, v128
	v_rcp_f32_e32 v129, v129
	v_add_f32_e32 v132, 1.0, v132
	v_rcp_f32_e32 v132, v132
	v_add_f32_e32 v130, 1.0, v130
	v_add_f32_e32 v131, 1.0, v131
	v_rcp_f32_e32 v130, v130
	v_rcp_f32_e32 v131, v131
	v_pk_fma_f32 v[128:129], v[128:129], s[36:37], 0.5 op_sel_hi:[1,0,0]
	v_pk_fma_f32 v[134:135], v[140:141], s[36:37], 0.5 op_sel_hi:[1,0,0]
	v_cvt_u32_f32_e32 v140, v128
	v_cvt_u32_f32_e32 v141, v129
	v_cvt_u32_f32_e32 v135, v135
	v_cvt_u32_f32_e32 v134, v134
	v_pk_fma_f32 v[128:129], v[132:133], s[36:37], 0.5 op_sel_hi:[1,0,0]
	s_nop 0
	v_cvt_u32_f32_sdwa v132, v128 dst_sel:WORD_1 dst_unused:UNUSED_PAD src0_sel:DWORD
	v_cvt_u32_f32_sdwa v133, v129 dst_sel:WORD_1 dst_unused:UNUSED_PAD src0_sel:DWORD
	v_pk_fma_f32 v[128:129], v[130:131], s[36:37], 0.5 op_sel_hi:[1,0,0]
	v_lshlrev_b32_e32 v130, 8, v141
	v_cvt_u32_f32_sdwa v128, v128 dst_sel:BYTE_3 dst_unused:UNUSED_PAD src0_sel:DWORD
	v_cvt_u32_f32_sdwa v129, v129 dst_sel:BYTE_3 dst_unused:UNUSED_PAD src0_sel:DWORD
	v_lshlrev_b32_e32 v131, 8, v140
	v_or_b32_e32 v130, v130, v135
	v_or_b32_e32 v131, v131, v134
	v_or_b32_e32 v130, v130, v133
	v_or_b32_e32 v131, v131, v132
	v_or_b32_e32 v129, v130, v129
	v_or_b32_e32 v128, v131, v128
	v_mov_b64_e32 v[244:245], v[128:129]
	v_or_b32_e32 v128, 16, v166
	v_ashrrev_i32_e32 v129, 31, v128
	v_lshlrev_b64 v[130:131], 6, v[128:129]
	v_lshl_add_u64 v[134:135], s[26:27], 0, v[130:131]
	s_nop 0
	s_nop 0
	s_nop 0
	s_nop 0
	v_mov_b32_e32 v129, v207
	v_fma_f32 v120, v120, v129, v40
	v_mul_f32_e32 v120, 0xbfb8aa3b, v120
	v_fma_f32 v124, v124, v129, v44
	v_exp_f32_e32 v120, v120
	v_mul_f32_e32 v124, 0xbfb8aa3b, v124
	v_fma_f32 v122, v122, v129, v42
	v_exp_f32_e32 v124, v124
	v_mul_f32_e32 v122, 0xbfb8aa3b, v122
	v_exp_f32_e32 v122, v122
	v_add_f32_e32 v120, 1.0, v120
	v_rcp_f32_e32 v131, v120
	v_fma_f32 v120, v125, v129, v45
	v_fma_f32 v121, v121, v129, v41
	v_add_f32_e32 v124, 1.0, v124
	v_mul_f32_e32 v120, 0xbfb8aa3b, v120
	v_mul_f32_e32 v121, 0xbfb8aa3b, v121
	v_rcp_f32_e32 v130, v124
	v_exp_f32_e32 v120, v120
	v_exp_f32_e32 v121, v121
	v_fma_f32 v124, v126, v129, v46
	v_add_f32_e32 v122, 1.0, v122
	v_mul_f32_e32 v124, 0xbfb8aa3b, v124
	v_rcp_f32_e32 v125, v122
	v_fma_f32 v122, v127, v129, v47
	v_fma_f32 v123, v123, v129, v43
	v_exp_f32_e32 v124, v124
	v_mul_f32_e32 v122, 0xbfb8aa3b, v122
	v_mul_f32_e32 v123, 0xbfb8aa3b, v123
	v_exp_f32_e32 v122, v122
	v_exp_f32_e32 v123, v123
	v_add_f32_e32 v120, 1.0, v120
	v_add_f32_e32 v121, 1.0, v121
	v_rcp_f32_e32 v120, v120
	v_rcp_f32_e32 v121, v121
	v_add_f32_e32 v124, 1.0, v124
	v_rcp_f32_e32 v124, v124
	v_add_f32_e32 v122, 1.0, v122
	v_add_f32_e32 v123, 1.0, v123
	v_rcp_f32_e32 v122, v122
	v_rcp_f32_e32 v123, v123
	v_pk_fma_f32 v[120:121], v[120:121], s[36:37], 0.5 op_sel_hi:[1,0,0]
	v_pk_fma_f32 v[126:127], v[130:131], s[36:37], 0.5 op_sel_hi:[1,0,0]
	v_cvt_u32_f32_e32 v130, v120
	v_cvt_u32_f32_e32 v131, v121
	v_cvt_u32_f32_e32 v127, v127
	v_cvt_u32_f32_e32 v126, v126
	v_pk_fma_f32 v[120:121], v[124:125], s[36:37], 0.5 op_sel_hi:[1,0,0]
	v_fma_f32 v112, v112, v129, v24
	v_cvt_u32_f32_sdwa v124, v120 dst_sel:WORD_1 dst_unused:UNUSED_PAD src0_sel:DWORD
	v_cvt_u32_f32_sdwa v125, v121 dst_sel:WORD_1 dst_unused:UNUSED_PAD src0_sel:DWORD
	v_pk_fma_f32 v[120:121], v[122:123], s[36:37], 0.5 op_sel_hi:[1,0,0]
	v_mul_f32_e32 v112, 0xbfb8aa3b, v112
	v_cvt_u32_f32_sdwa v120, v120 dst_sel:BYTE_3 dst_unused:UNUSED_PAD src0_sel:DWORD
	v_cvt_u32_f32_sdwa v121, v121 dst_sel:BYTE_3 dst_unused:UNUSED_PAD src0_sel:DWORD
	v_lshlrev_b32_e32 v122, 8, v131
	v_lshlrev_b32_e32 v123, 8, v130
	v_fma_f32 v116, v116, v129, v28
	v_exp_f32_e32 v112, v112
	v_or_b32_e32 v122, v122, v127
	v_or_b32_e32 v123, v123, v126
	v_mul_f32_e32 v116, 0xbfb8aa3b, v116
	v_fma_f32 v114, v114, v129, v26
	v_or_b32_e32 v122, v122, v125
	v_or_b32_e32 v124, v123, v124
	v_exp_f32_e32 v116, v116
	v_mul_f32_e32 v114, 0xbfb8aa3b, v114
	v_or_b32_e32 v123, v122, v121
	v_or_b32_e32 v122, v124, v120
	v_mad_i64_i32 v[120:121], s[18:19], v128, s28, v[136:137]
	v_exp_f32_e32 v114, v114
	v_lshl_add_u64 v[120:121], v[120:121], 0, v[164:165]
	v_add_f32_e32 v112, 1.0, v112
	v_mov_b64_e32 v[242:243], v[122:123]
	s_nop 1
	v_permlane16_swap_b32_e32 v240, v242
	v_permlane16_swap_b32_e32 v241, v243
	global_store_dwordx4 v[248:249], v[240:243], off
	v_rcp_f32_e32 v123, v112
	v_fma_f32 v112, v117, v129, v29
	v_fma_f32 v113, v113, v129, v25
	v_add_f32_e32 v116, 1.0, v116
	v_mul_f32_e32 v112, 0xbfb8aa3b, v112
	v_mul_f32_e32 v113, 0xbfb8aa3b, v113
	v_rcp_f32_e32 v122, v116
	v_exp_f32_e32 v112, v112
	v_exp_f32_e32 v113, v113
	v_fma_f32 v116, v118, v129, v30
	v_add_f32_e32 v114, 1.0, v114
	v_mul_f32_e32 v116, 0xbfb8aa3b, v116
	v_rcp_f32_e32 v117, v114
	v_fma_f32 v114, v119, v129, v31
	v_fma_f32 v115, v115, v129, v27
	v_exp_f32_e32 v116, v116
	v_mul_f32_e32 v114, 0xbfb8aa3b, v114
	v_mul_f32_e32 v115, 0xbfb8aa3b, v115
	v_exp_f32_e32 v114, v114
	v_exp_f32_e32 v115, v115
	v_add_f32_e32 v112, 1.0, v112
	v_add_f32_e32 v113, 1.0, v113
	v_rcp_f32_e32 v112, v112
	v_rcp_f32_e32 v113, v113
	v_add_f32_e32 v116, 1.0, v116
	v_rcp_f32_e32 v116, v116
	v_add_f32_e32 v114, 1.0, v114
	v_add_f32_e32 v115, 1.0, v115
	v_rcp_f32_e32 v114, v114
	v_rcp_f32_e32 v115, v115
	v_pk_fma_f32 v[112:113], v[112:113], s[36:37], 0.5 op_sel_hi:[1,0,0]
	v_pk_fma_f32 v[118:119], v[122:123], s[36:37], 0.5 op_sel_hi:[1,0,0]
	v_cvt_u32_f32_e32 v122, v112
	v_cvt_u32_f32_e32 v123, v113
	v_cvt_u32_f32_e32 v119, v119
	v_cvt_u32_f32_e32 v118, v118
	v_pk_fma_f32 v[112:113], v[116:117], s[36:37], 0.5 op_sel_hi:[1,0,0]
	s_nop 0
	v_cvt_u32_f32_sdwa v116, v112 dst_sel:WORD_1 dst_unused:UNUSED_PAD src0_sel:DWORD
	v_cvt_u32_f32_sdwa v117, v113 dst_sel:WORD_1 dst_unused:UNUSED_PAD src0_sel:DWORD
	v_pk_fma_f32 v[112:113], v[114:115], s[36:37], 0.5 op_sel_hi:[1,0,0]
	v_lshlrev_b32_e32 v114, 8, v123
	v_cvt_u32_f32_sdwa v112, v112 dst_sel:BYTE_3 dst_unused:UNUSED_PAD src0_sel:DWORD
	v_cvt_u32_f32_sdwa v113, v113 dst_sel:BYTE_3 dst_unused:UNUSED_PAD src0_sel:DWORD
	v_lshlrev_b32_e32 v115, 8, v122
	v_or_b32_e32 v114, v114, v119
	v_or_b32_e32 v115, v115, v118
	v_or_b32_e32 v114, v114, v117
	v_or_b32_e32 v115, v115, v116
	v_or_b32_e32 v113, v114, v113
	v_or_b32_e32 v112, v115, v112
	v_mov_b64_e32 v[246:247], v[112:113]
	s_nop 1
	v_permlane16_swap_b32_e32 v244, v246
	v_permlane16_swap_b32_e32 v245, v247
	global_store_dwordx4 v[248:249], v[244:247], off offset:128
	v_or_b32_e32 v112, 32, v166
	v_ashrrev_i32_e32 v113, 31, v112
	v_lshlrev_b64 v[114:115], 6, v[112:113]
	v_lshl_add_u64 v[126:127], s[26:27], 0, v[114:115]
	s_nop 0
	s_nop 0
	s_nop 0
	s_nop 0
	s_nop 0
	v_mov_b32_e32 v113, v215
	v_fma_f32 v104, v104, v113, v40
	v_mul_f32_e32 v104, 0xbfb8aa3b, v104
	v_fma_f32 v108, v108, v113, v44
	v_exp_f32_e32 v104, v104
	v_mul_f32_e32 v108, 0xbfb8aa3b, v108
	v_fma_f32 v106, v106, v113, v42
	v_exp_f32_e32 v108, v108
	v_mul_f32_e32 v106, 0xbfb8aa3b, v106
	v_exp_f32_e32 v106, v106
	v_add_f32_e32 v104, 1.0, v104
	v_rcp_f32_e32 v115, v104
	v_fma_f32 v104, v109, v113, v45
	v_fma_f32 v105, v105, v113, v41
	v_add_f32_e32 v108, 1.0, v108
	v_mul_f32_e32 v104, 0xbfb8aa3b, v104
	v_mul_f32_e32 v105, 0xbfb8aa3b, v105
	v_rcp_f32_e32 v114, v108
	v_exp_f32_e32 v104, v104
	v_exp_f32_e32 v105, v105
	v_fma_f32 v108, v110, v113, v46
	v_add_f32_e32 v106, 1.0, v106
	v_mul_f32_e32 v108, 0xbfb8aa3b, v108
	v_rcp_f32_e32 v109, v106
	v_fma_f32 v106, v111, v113, v47
	v_fma_f32 v107, v107, v113, v43
	v_exp_f32_e32 v108, v108
	v_mul_f32_e32 v106, 0xbfb8aa3b, v106
	v_mul_f32_e32 v107, 0xbfb8aa3b, v107
	v_exp_f32_e32 v106, v106
	v_exp_f32_e32 v107, v107
	v_add_f32_e32 v104, 1.0, v104
	v_add_f32_e32 v105, 1.0, v105
	v_rcp_f32_e32 v104, v104
	v_rcp_f32_e32 v105, v105
	v_add_f32_e32 v108, 1.0, v108
	v_rcp_f32_e32 v108, v108
	v_add_f32_e32 v106, 1.0, v106
	v_add_f32_e32 v107, 1.0, v107
	v_rcp_f32_e32 v106, v106
	v_rcp_f32_e32 v107, v107
	v_pk_fma_f32 v[104:105], v[104:105], s[36:37], 0.5 op_sel_hi:[1,0,0]
	v_pk_fma_f32 v[110:111], v[114:115], s[36:37], 0.5 op_sel_hi:[1,0,0]
	v_cvt_u32_f32_e32 v114, v104
	v_cvt_u32_f32_e32 v115, v105
	v_cvt_u32_f32_e32 v111, v111
	v_cvt_u32_f32_e32 v110, v110
	v_pk_fma_f32 v[104:105], v[108:109], s[36:37], 0.5 op_sel_hi:[1,0,0]
	v_fma_f32 v96, v96, v113, v24
	v_cvt_u32_f32_sdwa v108, v104 dst_sel:WORD_1 dst_unused:UNUSED_PAD src0_sel:DWORD
	v_cvt_u32_f32_sdwa v109, v105 dst_sel:WORD_1 dst_unused:UNUSED_PAD src0_sel:DWORD
	v_pk_fma_f32 v[104:105], v[106:107], s[36:37], 0.5 op_sel_hi:[1,0,0]
	v_mul_f32_e32 v96, 0xbfb8aa3b, v96
	v_cvt_u32_f32_sdwa v104, v104 dst_sel:BYTE_3 dst_unused:UNUSED_PAD src0_sel:DWORD
	v_cvt_u32_f32_sdwa v105, v105 dst_sel:BYTE_3 dst_unused:UNUSED_PAD src0_sel:DWORD
	v_lshlrev_b32_e32 v106, 8, v115
	v_lshlrev_b32_e32 v107, 8, v114
	v_fma_f32 v100, v100, v113, v28
	v_exp_f32_e32 v96, v96
	v_or_b32_e32 v106, v106, v111
	v_or_b32_e32 v107, v107, v110
	v_mul_f32_e32 v100, 0xbfb8aa3b, v100
	v_fma_f32 v98, v98, v113, v26
	v_or_b32_e32 v106, v106, v109
	v_or_b32_e32 v108, v107, v108
	v_exp_f32_e32 v100, v100
	v_mul_f32_e32 v98, 0xbfb8aa3b, v98
	v_or_b32_e32 v107, v106, v105
	v_or_b32_e32 v106, v108, v104
	v_mad_i64_i32 v[104:105], s[18:19], v112, s28, v[136:137]
	v_exp_f32_e32 v98, v98
	v_lshl_add_u64 v[104:105], v[104:105], 0, v[164:165]
	v_add_f32_e32 v96, 1.0, v96
	v_lshl_add_u64 v[248:249], v[104:105], 0, v[250:251]
	v_mov_b64_e32 v[240:241], v[106:107]
	v_rcp_f32_e32 v107, v96
	v_fma_f32 v96, v101, v113, v29
	v_fma_f32 v97, v97, v113, v25
	v_add_f32_e32 v100, 1.0, v100
	v_mul_f32_e32 v96, 0xbfb8aa3b, v96
	v_mul_f32_e32 v97, 0xbfb8aa3b, v97
	v_rcp_f32_e32 v106, v100
	v_exp_f32_e32 v96, v96
	v_exp_f32_e32 v97, v97
	v_fma_f32 v100, v102, v113, v30
	v_add_f32_e32 v98, 1.0, v98
	v_mul_f32_e32 v100, 0xbfb8aa3b, v100
	v_rcp_f32_e32 v101, v98
	v_fma_f32 v98, v103, v113, v31
	v_fma_f32 v99, v99, v113, v27
	v_exp_f32_e32 v100, v100
	v_mul_f32_e32 v98, 0xbfb8aa3b, v98
	v_mul_f32_e32 v99, 0xbfb8aa3b, v99
	v_exp_f32_e32 v98, v98
	v_exp_f32_e32 v99, v99
	v_add_f32_e32 v96, 1.0, v96
	v_add_f32_e32 v97, 1.0, v97
	v_rcp_f32_e32 v96, v96
	v_rcp_f32_e32 v97, v97
	v_add_f32_e32 v100, 1.0, v100
	v_rcp_f32_e32 v100, v100
	v_add_f32_e32 v98, 1.0, v98
	v_add_f32_e32 v99, 1.0, v99
	v_rcp_f32_e32 v98, v98
	v_rcp_f32_e32 v99, v99
	v_pk_fma_f32 v[96:97], v[96:97], s[36:37], 0.5 op_sel_hi:[1,0,0]
	v_pk_fma_f32 v[102:103], v[106:107], s[36:37], 0.5 op_sel_hi:[1,0,0]
	v_cvt_u32_f32_e32 v106, v96
	v_cvt_u32_f32_e32 v107, v97
	v_cvt_u32_f32_e32 v103, v103
	v_cvt_u32_f32_e32 v102, v102
	v_pk_fma_f32 v[96:97], v[100:101], s[36:37], 0.5 op_sel_hi:[1,0,0]
	s_nop 0
	v_cvt_u32_f32_sdwa v100, v96 dst_sel:WORD_1 dst_unused:UNUSED_PAD src0_sel:DWORD
	v_cvt_u32_f32_sdwa v101, v97 dst_sel:WORD_1 dst_unused:UNUSED_PAD src0_sel:DWORD
	v_pk_fma_f32 v[96:97], v[98:99], s[36:37], 0.5 op_sel_hi:[1,0,0]
	v_lshlrev_b32_e32 v98, 8, v107
	v_cvt_u32_f32_sdwa v96, v96 dst_sel:BYTE_3 dst_unused:UNUSED_PAD src0_sel:DWORD
	v_cvt_u32_f32_sdwa v97, v97 dst_sel:BYTE_3 dst_unused:UNUSED_PAD src0_sel:DWORD
	v_lshlrev_b32_e32 v99, 8, v106
	v_or_b32_e32 v98, v98, v103
	v_or_b32_e32 v99, v99, v102
	v_or_b32_e32 v98, v98, v101
	v_or_b32_e32 v99, v99, v100
	v_or_b32_e32 v97, v98, v97
	v_or_b32_e32 v96, v99, v96
	v_mov_b64_e32 v[244:245], v[96:97]
	v_or_b32_e32 v96, 48, v166
	v_ashrrev_i32_e32 v97, 31, v96
	v_lshlrev_b64 v[98:99], 6, v[96:97]
	v_lshl_add_u64 v[110:111], s[26:27], 0, v[98:99]
	s_nop 0
	s_nop 0
	s_nop 0
	s_nop 0
	s_nop 0
	v_mov_b32_e32 v97, v219
	v_fma_f32 v88, v88, v97, v40
	v_mul_f32_e32 v88, 0xbfb8aa3b, v88
	v_fma_f32 v92, v92, v97, v44
	v_exp_f32_e32 v88, v88
	v_mul_f32_e32 v92, 0xbfb8aa3b, v92
	v_fma_f32 v90, v90, v97, v42
	v_exp_f32_e32 v92, v92
	v_mul_f32_e32 v90, 0xbfb8aa3b, v90
	v_exp_f32_e32 v90, v90
	v_add_f32_e32 v88, 1.0, v88
	v_rcp_f32_e32 v99, v88
	v_fma_f32 v88, v93, v97, v45
	v_fma_f32 v89, v89, v97, v41
	v_add_f32_e32 v92, 1.0, v92
	v_mul_f32_e32 v88, 0xbfb8aa3b, v88
	v_mul_f32_e32 v89, 0xbfb8aa3b, v89
	v_rcp_f32_e32 v98, v92
	v_exp_f32_e32 v88, v88
	v_exp_f32_e32 v89, v89
	v_fma_f32 v92, v94, v97, v46
	v_add_f32_e32 v90, 1.0, v90
	v_mul_f32_e32 v92, 0xbfb8aa3b, v92
	v_rcp_f32_e32 v93, v90
	v_fma_f32 v90, v95, v97, v47
	v_fma_f32 v91, v91, v97, v43
	v_exp_f32_e32 v92, v92
	v_mul_f32_e32 v90, 0xbfb8aa3b, v90
	v_mul_f32_e32 v91, 0xbfb8aa3b, v91
	v_exp_f32_e32 v90, v90
	v_exp_f32_e32 v91, v91
	v_add_f32_e32 v88, 1.0, v88
	v_add_f32_e32 v89, 1.0, v89
	v_rcp_f32_e32 v88, v88
	v_rcp_f32_e32 v89, v89
	v_add_f32_e32 v92, 1.0, v92
	v_rcp_f32_e32 v92, v92
	v_add_f32_e32 v90, 1.0, v90
	v_add_f32_e32 v91, 1.0, v91
	v_rcp_f32_e32 v90, v90
	v_rcp_f32_e32 v91, v91
	v_pk_fma_f32 v[88:89], v[88:89], s[36:37], 0.5 op_sel_hi:[1,0,0]
	v_pk_fma_f32 v[94:95], v[98:99], s[36:37], 0.5 op_sel_hi:[1,0,0]
	v_cvt_u32_f32_e32 v98, v88
	v_cvt_u32_f32_e32 v99, v89
	v_cvt_u32_f32_e32 v95, v95
	v_cvt_u32_f32_e32 v94, v94
	v_pk_fma_f32 v[88:89], v[92:93], s[36:37], 0.5 op_sel_hi:[1,0,0]
	v_fma_f32 v80, v80, v97, v24
	v_cvt_u32_f32_sdwa v92, v88 dst_sel:WORD_1 dst_unused:UNUSED_PAD src0_sel:DWORD
	v_cvt_u32_f32_sdwa v93, v89 dst_sel:WORD_1 dst_unused:UNUSED_PAD src0_sel:DWORD
	v_pk_fma_f32 v[88:89], v[90:91], s[36:37], 0.5 op_sel_hi:[1,0,0]
	v_mul_f32_e32 v80, 0xbfb8aa3b, v80
	v_cvt_u32_f32_sdwa v88, v88 dst_sel:BYTE_3 dst_unused:UNUSED_PAD src0_sel:DWORD
	v_cvt_u32_f32_sdwa v89, v89 dst_sel:BYTE_3 dst_unused:UNUSED_PAD src0_sel:DWORD
	v_lshlrev_b32_e32 v90, 8, v99
	v_lshlrev_b32_e32 v91, 8, v98
	v_fma_f32 v84, v84, v97, v28
	v_exp_f32_e32 v80, v80
	v_or_b32_e32 v90, v90, v95
	v_or_b32_e32 v91, v91, v94
	v_mul_f32_e32 v84, 0xbfb8aa3b, v84
	v_fma_f32 v82, v82, v97, v26
	v_or_b32_e32 v90, v90, v93
	v_or_b32_e32 v92, v91, v92
	v_exp_f32_e32 v84, v84
	v_mul_f32_e32 v82, 0xbfb8aa3b, v82
	v_or_b32_e32 v91, v90, v89
	v_or_b32_e32 v90, v92, v88
	v_mad_i64_i32 v[88:89], s[18:19], v96, s28, v[136:137]
	v_exp_f32_e32 v82, v82
	v_lshl_add_u64 v[88:89], v[88:89], 0, v[164:165]
	v_add_f32_e32 v80, 1.0, v80
	v_mov_b64_e32 v[242:243], v[90:91]
	s_nop 1
	v_permlane16_swap_b32_e32 v240, v242
	v_permlane16_swap_b32_e32 v241, v243
	global_store_dwordx4 v[248:249], v[240:243], off
	v_rcp_f32_e32 v91, v80
	v_fma_f32 v80, v85, v97, v29
	v_fma_f32 v81, v81, v97, v25
	v_add_f32_e32 v84, 1.0, v84
	v_mul_f32_e32 v80, 0xbfb8aa3b, v80
	v_mul_f32_e32 v81, 0xbfb8aa3b, v81
	v_rcp_f32_e32 v90, v84
	v_exp_f32_e32 v80, v80
	v_exp_f32_e32 v81, v81
	v_fma_f32 v84, v86, v97, v30
	v_add_f32_e32 v82, 1.0, v82
	v_mul_f32_e32 v84, 0xbfb8aa3b, v84
	v_rcp_f32_e32 v85, v82
	v_fma_f32 v82, v87, v97, v31
	v_fma_f32 v83, v83, v97, v27
	v_exp_f32_e32 v84, v84
	v_mul_f32_e32 v82, 0xbfb8aa3b, v82
	v_mul_f32_e32 v83, 0xbfb8aa3b, v83
	v_exp_f32_e32 v82, v82
	v_exp_f32_e32 v83, v83
	v_add_f32_e32 v80, 1.0, v80
	v_add_f32_e32 v81, 1.0, v81
	v_rcp_f32_e32 v80, v80
	v_rcp_f32_e32 v81, v81
	v_add_f32_e32 v84, 1.0, v84
	v_rcp_f32_e32 v84, v84
	v_add_f32_e32 v82, 1.0, v82
	v_add_f32_e32 v83, 1.0, v83
	v_rcp_f32_e32 v82, v82
	v_rcp_f32_e32 v83, v83
	v_pk_fma_f32 v[80:81], v[80:81], s[36:37], 0.5 op_sel_hi:[1,0,0]
	v_pk_fma_f32 v[86:87], v[90:91], s[36:37], 0.5 op_sel_hi:[1,0,0]
	v_cvt_u32_f32_e32 v90, v80
	v_cvt_u32_f32_e32 v91, v81
	v_cvt_u32_f32_e32 v87, v87
	v_cvt_u32_f32_e32 v86, v86
	v_pk_fma_f32 v[80:81], v[84:85], s[36:37], 0.5 op_sel_hi:[1,0,0]
	s_nop 0
	v_cvt_u32_f32_sdwa v84, v80 dst_sel:WORD_1 dst_unused:UNUSED_PAD src0_sel:DWORD
	v_cvt_u32_f32_sdwa v85, v81 dst_sel:WORD_1 dst_unused:UNUSED_PAD src0_sel:DWORD
	v_pk_fma_f32 v[80:81], v[82:83], s[36:37], 0.5 op_sel_hi:[1,0,0]
	v_lshlrev_b32_e32 v82, 8, v91
	v_cvt_u32_f32_sdwa v80, v80 dst_sel:BYTE_3 dst_unused:UNUSED_PAD src0_sel:DWORD
	v_cvt_u32_f32_sdwa v81, v81 dst_sel:BYTE_3 dst_unused:UNUSED_PAD src0_sel:DWORD
	v_lshlrev_b32_e32 v83, 8, v90
	v_or_b32_e32 v82, v82, v87
	v_or_b32_e32 v83, v83, v86
	v_or_b32_e32 v82, v82, v85
	v_or_b32_e32 v83, v83, v84
	v_or_b32_e32 v81, v82, v81
	v_or_b32_e32 v80, v83, v80
	v_mov_b64_e32 v[246:247], v[80:81]
	s_nop 1
	v_permlane16_swap_b32_e32 v244, v246
	v_permlane16_swap_b32_e32 v245, v247
	global_store_dwordx4 v[248:249], v[244:247], off offset:128
	v_add_u32_e32 v80, 0x80, v166
	v_ashrrev_i32_e32 v81, 31, v80
	v_lshlrev_b64 v[82:83], 6, v[80:81]
	v_lshl_add_u64 v[94:95], s[26:27], 0, v[82:83]
	s_nop 0
	s_nop 0
	s_nop 0
	s_nop 0
	s_nop 0
	v_mov_b32_e32 v81, v223
	v_fma_f32 v72, v72, v81, v40
	v_mul_f32_e32 v72, 0xbfb8aa3b, v72
	v_fma_f32 v76, v76, v81, v44
	v_exp_f32_e32 v72, v72
	v_mul_f32_e32 v76, 0xbfb8aa3b, v76
	v_fma_f32 v74, v74, v81, v42
	v_exp_f32_e32 v76, v76
	v_mul_f32_e32 v74, 0xbfb8aa3b, v74
	v_exp_f32_e32 v74, v74
	v_add_f32_e32 v72, 1.0, v72
	v_rcp_f32_e32 v83, v72
	v_fma_f32 v72, v77, v81, v45
	v_fma_f32 v73, v73, v81, v41
	v_add_f32_e32 v76, 1.0, v76
	v_mul_f32_e32 v72, 0xbfb8aa3b, v72
	v_mul_f32_e32 v73, 0xbfb8aa3b, v73
	v_rcp_f32_e32 v82, v76
	v_exp_f32_e32 v72, v72
	v_exp_f32_e32 v73, v73
	v_fma_f32 v76, v78, v81, v46
	v_add_f32_e32 v74, 1.0, v74
	v_mul_f32_e32 v76, 0xbfb8aa3b, v76
	v_rcp_f32_e32 v77, v74
	v_fma_f32 v74, v79, v81, v47
	v_fma_f32 v75, v75, v81, v43
	v_exp_f32_e32 v76, v76
	v_mul_f32_e32 v74, 0xbfb8aa3b, v74
	v_mul_f32_e32 v75, 0xbfb8aa3b, v75
	v_exp_f32_e32 v74, v74
	v_exp_f32_e32 v75, v75
	v_add_f32_e32 v72, 1.0, v72
	v_add_f32_e32 v73, 1.0, v73
	v_rcp_f32_e32 v72, v72
	v_rcp_f32_e32 v73, v73
	v_add_f32_e32 v76, 1.0, v76
	v_rcp_f32_e32 v76, v76
	v_add_f32_e32 v74, 1.0, v74
	v_add_f32_e32 v75, 1.0, v75
	v_rcp_f32_e32 v74, v74
	v_rcp_f32_e32 v75, v75
	v_pk_fma_f32 v[72:73], v[72:73], s[36:37], 0.5 op_sel_hi:[1,0,0]
	v_pk_fma_f32 v[78:79], v[82:83], s[36:37], 0.5 op_sel_hi:[1,0,0]
	v_cvt_u32_f32_e32 v82, v72
	v_cvt_u32_f32_e32 v83, v73
	v_cvt_u32_f32_e32 v79, v79
	v_cvt_u32_f32_e32 v78, v78
	v_pk_fma_f32 v[72:73], v[76:77], s[36:37], 0.5 op_sel_hi:[1,0,0]
	v_fma_f32 v64, v64, v81, v24
	v_cvt_u32_f32_sdwa v76, v72 dst_sel:WORD_1 dst_unused:UNUSED_PAD src0_sel:DWORD
	v_cvt_u32_f32_sdwa v77, v73 dst_sel:WORD_1 dst_unused:UNUSED_PAD src0_sel:DWORD
	v_pk_fma_f32 v[72:73], v[74:75], s[36:37], 0.5 op_sel_hi:[1,0,0]
	v_mul_f32_e32 v64, 0xbfb8aa3b, v64
	v_cvt_u32_f32_sdwa v72, v72 dst_sel:BYTE_3 dst_unused:UNUSED_PAD src0_sel:DWORD
	v_cvt_u32_f32_sdwa v73, v73 dst_sel:BYTE_3 dst_unused:UNUSED_PAD src0_sel:DWORD
	v_lshlrev_b32_e32 v74, 8, v83
	v_lshlrev_b32_e32 v75, 8, v82
	v_fma_f32 v68, v68, v81, v28
	v_exp_f32_e32 v64, v64
	v_or_b32_e32 v74, v74, v79
	v_or_b32_e32 v75, v75, v78
	v_mul_f32_e32 v68, 0xbfb8aa3b, v68
	v_fma_f32 v66, v66, v81, v26
	v_or_b32_e32 v74, v74, v77
	v_or_b32_e32 v76, v75, v76
	v_exp_f32_e32 v68, v68
	v_mul_f32_e32 v66, 0xbfb8aa3b, v66
	v_or_b32_e32 v75, v74, v73
	v_or_b32_e32 v74, v76, v72
	v_mad_i64_i32 v[72:73], s[18:19], v80, s28, v[136:137]
	v_exp_f32_e32 v66, v66
	v_lshl_add_u64 v[72:73], v[72:73], 0, v[164:165]
	v_add_f32_e32 v64, 1.0, v64
	v_lshl_add_u64 v[248:249], v[72:73], 0, v[250:251]
	v_mov_b64_e32 v[240:241], v[74:75]
	v_rcp_f32_e32 v75, v64
	v_fma_f32 v64, v69, v81, v29
	v_fma_f32 v65, v65, v81, v25
	v_add_f32_e32 v68, 1.0, v68
	v_mul_f32_e32 v64, 0xbfb8aa3b, v64
	v_mul_f32_e32 v65, 0xbfb8aa3b, v65
	v_rcp_f32_e32 v74, v68
	v_exp_f32_e32 v64, v64
	v_exp_f32_e32 v65, v65
	v_fma_f32 v68, v70, v81, v30
	v_add_f32_e32 v66, 1.0, v66
	v_mul_f32_e32 v68, 0xbfb8aa3b, v68
	v_rcp_f32_e32 v69, v66
	v_fma_f32 v66, v71, v81, v31
	v_fma_f32 v67, v67, v81, v27
	v_exp_f32_e32 v68, v68
	v_mul_f32_e32 v66, 0xbfb8aa3b, v66
	v_mul_f32_e32 v67, 0xbfb8aa3b, v67
	v_exp_f32_e32 v66, v66
	v_exp_f32_e32 v67, v67
	v_add_f32_e32 v64, 1.0, v64
	v_add_f32_e32 v65, 1.0, v65
	v_rcp_f32_e32 v64, v64
	v_rcp_f32_e32 v65, v65
	v_add_f32_e32 v68, 1.0, v68
	v_rcp_f32_e32 v68, v68
	v_add_f32_e32 v66, 1.0, v66
	v_add_f32_e32 v67, 1.0, v67
	v_rcp_f32_e32 v66, v66
	v_rcp_f32_e32 v67, v67
	v_pk_fma_f32 v[64:65], v[64:65], s[36:37], 0.5 op_sel_hi:[1,0,0]
	v_pk_fma_f32 v[70:71], v[74:75], s[36:37], 0.5 op_sel_hi:[1,0,0]
	v_cvt_u32_f32_e32 v74, v64
	v_cvt_u32_f32_e32 v75, v65
	v_cvt_u32_f32_e32 v71, v71
	v_cvt_u32_f32_e32 v70, v70
	v_pk_fma_f32 v[64:65], v[68:69], s[36:37], 0.5 op_sel_hi:[1,0,0]
	s_nop 0
	v_cvt_u32_f32_sdwa v68, v64 dst_sel:WORD_1 dst_unused:UNUSED_PAD src0_sel:DWORD
	v_cvt_u32_f32_sdwa v69, v65 dst_sel:WORD_1 dst_unused:UNUSED_PAD src0_sel:DWORD
	v_pk_fma_f32 v[64:65], v[66:67], s[36:37], 0.5 op_sel_hi:[1,0,0]
	v_lshlrev_b32_e32 v66, 8, v75
	v_cvt_u32_f32_sdwa v64, v64 dst_sel:BYTE_3 dst_unused:UNUSED_PAD src0_sel:DWORD
	v_cvt_u32_f32_sdwa v65, v65 dst_sel:BYTE_3 dst_unused:UNUSED_PAD src0_sel:DWORD
	v_lshlrev_b32_e32 v67, 8, v74
	v_or_b32_e32 v66, v66, v71
	v_or_b32_e32 v67, v67, v70
	v_or_b32_e32 v66, v66, v69
	v_or_b32_e32 v67, v67, v68
	v_or_b32_e32 v65, v66, v65
	v_or_b32_e32 v64, v67, v64
	v_mov_b64_e32 v[244:245], v[64:65]
	v_add_u32_e32 v64, 0x90, v166
	v_ashrrev_i32_e32 v65, 31, v64
	v_lshlrev_b64 v[66:67], 6, v[64:65]
	v_lshl_add_u64 v[78:79], s[26:27], 0, v[66:67]
	s_nop 0
	s_nop 0
	s_nop 0
	s_nop 0
	s_nop 0
	v_mov_b32_e32 v65, v227
	v_fma_f32 v56, v56, v65, v40
	v_mul_f32_e32 v56, 0xbfb8aa3b, v56
	v_fma_f32 v60, v60, v65, v44
	v_exp_f32_e32 v56, v56
	v_mul_f32_e32 v60, 0xbfb8aa3b, v60
	v_fma_f32 v58, v58, v65, v42
	v_exp_f32_e32 v60, v60
	v_mul_f32_e32 v58, 0xbfb8aa3b, v58
	v_exp_f32_e32 v58, v58
	v_add_f32_e32 v56, 1.0, v56
	v_rcp_f32_e32 v67, v56
	v_fma_f32 v56, v61, v65, v45
	v_fma_f32 v57, v57, v65, v41
	v_add_f32_e32 v60, 1.0, v60
	v_mul_f32_e32 v56, 0xbfb8aa3b, v56
	v_mul_f32_e32 v57, 0xbfb8aa3b, v57
	v_rcp_f32_e32 v66, v60
	v_exp_f32_e32 v56, v56
	v_exp_f32_e32 v57, v57
	v_fma_f32 v60, v62, v65, v46
	v_add_f32_e32 v58, 1.0, v58
	v_mul_f32_e32 v60, 0xbfb8aa3b, v60
	v_rcp_f32_e32 v61, v58
	v_fma_f32 v58, v63, v65, v47
	v_fma_f32 v59, v59, v65, v43
	v_exp_f32_e32 v60, v60
	v_mul_f32_e32 v58, 0xbfb8aa3b, v58
	v_mul_f32_e32 v59, 0xbfb8aa3b, v59
	v_exp_f32_e32 v58, v58
	v_exp_f32_e32 v59, v59
	v_add_f32_e32 v56, 1.0, v56
	v_add_f32_e32 v57, 1.0, v57
	v_rcp_f32_e32 v56, v56
	v_rcp_f32_e32 v57, v57
	v_add_f32_e32 v60, 1.0, v60
	v_rcp_f32_e32 v60, v60
	v_add_f32_e32 v58, 1.0, v58
	v_add_f32_e32 v59, 1.0, v59
	v_rcp_f32_e32 v58, v58
	v_rcp_f32_e32 v59, v59
	v_pk_fma_f32 v[56:57], v[56:57], s[36:37], 0.5 op_sel_hi:[1,0,0]
	v_pk_fma_f32 v[62:63], v[66:67], s[36:37], 0.5 op_sel_hi:[1,0,0]
	v_cvt_u32_f32_e32 v66, v56
	v_cvt_u32_f32_e32 v67, v57
	v_cvt_u32_f32_e32 v63, v63
	v_cvt_u32_f32_e32 v62, v62
	v_pk_fma_f32 v[56:57], v[60:61], s[36:37], 0.5 op_sel_hi:[1,0,0]
	v_fma_f32 v48, v48, v65, v24
	v_cvt_u32_f32_sdwa v60, v56 dst_sel:WORD_1 dst_unused:UNUSED_PAD src0_sel:DWORD
	v_cvt_u32_f32_sdwa v61, v57 dst_sel:WORD_1 dst_unused:UNUSED_PAD src0_sel:DWORD
	v_pk_fma_f32 v[56:57], v[58:59], s[36:37], 0.5 op_sel_hi:[1,0,0]
	v_mul_f32_e32 v48, 0xbfb8aa3b, v48
	v_cvt_u32_f32_sdwa v56, v56 dst_sel:BYTE_3 dst_unused:UNUSED_PAD src0_sel:DWORD
	v_cvt_u32_f32_sdwa v57, v57 dst_sel:BYTE_3 dst_unused:UNUSED_PAD src0_sel:DWORD
	v_lshlrev_b32_e32 v58, 8, v67
	v_lshlrev_b32_e32 v59, 8, v66
	v_fma_f32 v52, v52, v65, v28
	v_exp_f32_e32 v48, v48
	v_or_b32_e32 v58, v58, v63
	v_or_b32_e32 v59, v59, v62
	v_mul_f32_e32 v52, 0xbfb8aa3b, v52
	v_fma_f32 v50, v50, v65, v26
	v_or_b32_e32 v58, v58, v61
	v_or_b32_e32 v60, v59, v60
	v_exp_f32_e32 v52, v52
	v_mul_f32_e32 v50, 0xbfb8aa3b, v50
	v_or_b32_e32 v59, v58, v57
	v_or_b32_e32 v58, v60, v56
	v_mad_i64_i32 v[56:57], s[18:19], v64, s28, v[136:137]
	v_exp_f32_e32 v50, v50
	v_lshl_add_u64 v[56:57], v[56:57], 0, v[164:165]
	v_add_f32_e32 v48, 1.0, v48
	v_mov_b64_e32 v[242:243], v[58:59]
	s_nop 1
	v_permlane16_swap_b32_e32 v240, v242
	v_permlane16_swap_b32_e32 v241, v243
	global_store_dwordx4 v[248:249], v[240:243], off
	v_rcp_f32_e32 v59, v48
	v_fma_f32 v48, v53, v65, v29
	v_fma_f32 v49, v49, v65, v25
	v_add_f32_e32 v52, 1.0, v52
	v_mul_f32_e32 v48, 0xbfb8aa3b, v48
	v_mul_f32_e32 v49, 0xbfb8aa3b, v49
	v_rcp_f32_e32 v58, v52
	v_exp_f32_e32 v48, v48
	v_exp_f32_e32 v49, v49
	v_fma_f32 v52, v54, v65, v30
	v_add_f32_e32 v50, 1.0, v50
	v_mul_f32_e32 v52, 0xbfb8aa3b, v52
	v_rcp_f32_e32 v53, v50
	v_fma_f32 v50, v55, v65, v31
	v_fma_f32 v51, v51, v65, v27
	v_exp_f32_e32 v52, v52
	v_mul_f32_e32 v50, 0xbfb8aa3b, v50
	v_mul_f32_e32 v51, 0xbfb8aa3b, v51
	v_exp_f32_e32 v50, v50
	v_exp_f32_e32 v51, v51
	v_add_f32_e32 v48, 1.0, v48
	v_add_f32_e32 v49, 1.0, v49
	v_rcp_f32_e32 v48, v48
	v_rcp_f32_e32 v49, v49
	v_add_f32_e32 v52, 1.0, v52
	v_rcp_f32_e32 v52, v52
	v_add_f32_e32 v50, 1.0, v50
	v_add_f32_e32 v51, 1.0, v51
	v_rcp_f32_e32 v50, v50
	v_rcp_f32_e32 v51, v51
	v_pk_fma_f32 v[48:49], v[48:49], s[36:37], 0.5 op_sel_hi:[1,0,0]
	v_pk_fma_f32 v[54:55], v[58:59], s[36:37], 0.5 op_sel_hi:[1,0,0]
	v_cvt_u32_f32_e32 v58, v48
	v_cvt_u32_f32_e32 v59, v49
	v_cvt_u32_f32_e32 v55, v55
	v_cvt_u32_f32_e32 v54, v54
	v_pk_fma_f32 v[48:49], v[52:53], s[36:37], 0.5 op_sel_hi:[1,0,0]
	s_nop 0
	v_cvt_u32_f32_sdwa v52, v48 dst_sel:WORD_1 dst_unused:UNUSED_PAD src0_sel:DWORD
	v_cvt_u32_f32_sdwa v53, v49 dst_sel:WORD_1 dst_unused:UNUSED_PAD src0_sel:DWORD
	v_pk_fma_f32 v[48:49], v[50:51], s[36:37], 0.5 op_sel_hi:[1,0,0]
	v_lshlrev_b32_e32 v50, 8, v59
	v_cvt_u32_f32_sdwa v48, v48 dst_sel:BYTE_3 dst_unused:UNUSED_PAD src0_sel:DWORD
	v_cvt_u32_f32_sdwa v49, v49 dst_sel:BYTE_3 dst_unused:UNUSED_PAD src0_sel:DWORD
	v_lshlrev_b32_e32 v51, 8, v58
	v_or_b32_e32 v50, v50, v55
	v_or_b32_e32 v51, v51, v54
	v_or_b32_e32 v50, v50, v53
	v_or_b32_e32 v51, v51, v52
	v_or_b32_e32 v49, v50, v49
	v_or_b32_e32 v48, v51, v48
	v_mov_b64_e32 v[246:247], v[48:49]
	s_nop 1
	v_permlane16_swap_b32_e32 v244, v246
	v_permlane16_swap_b32_e32 v245, v247
	global_store_dwordx4 v[248:249], v[244:247], off offset:128
	v_add_u32_e32 v48, 0xa0, v166
	v_ashrrev_i32_e32 v49, 31, v48
	v_lshlrev_b64 v[50:51], 6, v[48:49]
	v_lshl_add_u64 v[62:63], s[26:27], 0, v[50:51]
	s_nop 0
	s_nop 0
	s_nop 0
	s_nop 0
	s_nop 0
	v_mov_b32_e32 v49, v231
	v_fma_f32 v32, v32, v49, v40
	v_mul_f32_e32 v32, 0xbfb8aa3b, v32
	v_fma_f32 v36, v36, v49, v44
	v_exp_f32_e32 v32, v32
	v_mul_f32_e32 v36, 0xbfb8aa3b, v36
	v_fma_f32 v34, v34, v49, v42
	v_exp_f32_e32 v36, v36
	v_mul_f32_e32 v34, 0xbfb8aa3b, v34
	v_exp_f32_e32 v34, v34
	v_add_f32_e32 v32, 1.0, v32
	v_rcp_f32_e32 v51, v32
	v_fma_f32 v32, v37, v49, v45
	v_fma_f32 v33, v33, v49, v41
	v_add_f32_e32 v36, 1.0, v36
	v_mul_f32_e32 v32, 0xbfb8aa3b, v32
	v_mul_f32_e32 v33, 0xbfb8aa3b, v33
	v_rcp_f32_e32 v50, v36
	v_exp_f32_e32 v32, v32
	v_exp_f32_e32 v33, v33
	v_fma_f32 v36, v38, v49, v46
	v_add_f32_e32 v34, 1.0, v34
	v_mul_f32_e32 v36, 0xbfb8aa3b, v36
	v_rcp_f32_e32 v37, v34
	v_fma_f32 v34, v39, v49, v47
	v_fma_f32 v35, v35, v49, v43
	v_exp_f32_e32 v36, v36
	v_mul_f32_e32 v34, 0xbfb8aa3b, v34
	v_mul_f32_e32 v35, 0xbfb8aa3b, v35
	v_exp_f32_e32 v34, v34
	v_exp_f32_e32 v35, v35
	v_add_f32_e32 v32, 1.0, v32
	v_add_f32_e32 v33, 1.0, v33
	v_rcp_f32_e32 v32, v32
	v_rcp_f32_e32 v33, v33
	v_add_f32_e32 v36, 1.0, v36
	v_rcp_f32_e32 v36, v36
	v_add_f32_e32 v34, 1.0, v34
	v_add_f32_e32 v35, 1.0, v35
	v_rcp_f32_e32 v34, v34
	v_rcp_f32_e32 v35, v35
	v_pk_fma_f32 v[32:33], v[32:33], s[36:37], 0.5 op_sel_hi:[1,0,0]
	v_pk_fma_f32 v[38:39], v[50:51], s[36:37], 0.5 op_sel_hi:[1,0,0]
	v_cvt_u32_f32_e32 v50, v32
	v_cvt_u32_f32_e32 v51, v33
	v_cvt_u32_f32_e32 v39, v39
	v_cvt_u32_f32_e32 v38, v38
	v_pk_fma_f32 v[32:33], v[36:37], s[36:37], 0.5 op_sel_hi:[1,0,0]
	v_fma_f32 v16, v16, v49, v24
	v_cvt_u32_f32_sdwa v36, v32 dst_sel:WORD_1 dst_unused:UNUSED_PAD src0_sel:DWORD
	v_cvt_u32_f32_sdwa v37, v33 dst_sel:WORD_1 dst_unused:UNUSED_PAD src0_sel:DWORD
	v_pk_fma_f32 v[32:33], v[34:35], s[36:37], 0.5 op_sel_hi:[1,0,0]
	v_mul_f32_e32 v16, 0xbfb8aa3b, v16
	v_cvt_u32_f32_sdwa v32, v32 dst_sel:BYTE_3 dst_unused:UNUSED_PAD src0_sel:DWORD
	v_cvt_u32_f32_sdwa v33, v33 dst_sel:BYTE_3 dst_unused:UNUSED_PAD src0_sel:DWORD
	v_lshlrev_b32_e32 v34, 8, v51
	v_lshlrev_b32_e32 v35, 8, v50
	v_fma_f32 v20, v20, v49, v28
	v_exp_f32_e32 v16, v16
	v_or_b32_e32 v34, v34, v39
	v_or_b32_e32 v35, v35, v38
	v_mul_f32_e32 v20, 0xbfb8aa3b, v20
	v_fma_f32 v18, v18, v49, v26
	v_or_b32_e32 v34, v34, v37
	v_or_b32_e32 v36, v35, v36
	v_exp_f32_e32 v20, v20
	v_mul_f32_e32 v18, 0xbfb8aa3b, v18
	v_or_b32_e32 v35, v34, v33
	v_or_b32_e32 v34, v36, v32
	v_mad_i64_i32 v[32:33], s[18:19], v48, s28, v[136:137]
	v_exp_f32_e32 v18, v18
	v_lshl_add_u64 v[32:33], v[32:33], 0, v[164:165]
	v_add_f32_e32 v16, 1.0, v16
	v_lshl_add_u64 v[248:249], v[32:33], 0, v[250:251]
	v_mov_b64_e32 v[240:241], v[34:35]
	v_rcp_f32_e32 v35, v16
	v_fma_f32 v16, v21, v49, v29
	v_fma_f32 v17, v17, v49, v25
	v_add_f32_e32 v20, 1.0, v20
	v_mul_f32_e32 v16, 0xbfb8aa3b, v16
	v_mul_f32_e32 v17, 0xbfb8aa3b, v17
	v_rcp_f32_e32 v34, v20
	v_exp_f32_e32 v16, v16
	v_exp_f32_e32 v17, v17
	v_fma_f32 v20, v22, v49, v30
	v_add_f32_e32 v18, 1.0, v18
	v_mul_f32_e32 v20, 0xbfb8aa3b, v20
	v_rcp_f32_e32 v21, v18
	v_fma_f32 v18, v23, v49, v31
	v_fma_f32 v19, v19, v49, v27
	v_exp_f32_e32 v20, v20
	v_mul_f32_e32 v18, 0xbfb8aa3b, v18
	v_mul_f32_e32 v19, 0xbfb8aa3b, v19
	v_exp_f32_e32 v18, v18
	v_exp_f32_e32 v19, v19
	v_add_f32_e32 v16, 1.0, v16
	v_add_f32_e32 v17, 1.0, v17
	v_rcp_f32_e32 v16, v16
	v_rcp_f32_e32 v17, v17
	v_add_f32_e32 v20, 1.0, v20
	v_rcp_f32_e32 v20, v20
	v_add_f32_e32 v18, 1.0, v18
	v_add_f32_e32 v19, 1.0, v19
	v_rcp_f32_e32 v18, v18
	v_rcp_f32_e32 v19, v19
	v_pk_fma_f32 v[16:17], v[16:17], s[36:37], 0.5 op_sel_hi:[1,0,0]
	v_pk_fma_f32 v[22:23], v[34:35], s[36:37], 0.5 op_sel_hi:[1,0,0]
	v_cvt_u32_f32_e32 v34, v16
	v_cvt_u32_f32_e32 v35, v17
	v_cvt_u32_f32_e32 v23, v23
	v_cvt_u32_f32_e32 v22, v22
	v_pk_fma_f32 v[16:17], v[20:21], s[36:37], 0.5 op_sel_hi:[1,0,0]
	s_nop 0
	v_cvt_u32_f32_sdwa v20, v16 dst_sel:WORD_1 dst_unused:UNUSED_PAD src0_sel:DWORD
	v_cvt_u32_f32_sdwa v21, v17 dst_sel:WORD_1 dst_unused:UNUSED_PAD src0_sel:DWORD
	v_pk_fma_f32 v[16:17], v[18:19], s[36:37], 0.5 op_sel_hi:[1,0,0]
	v_lshlrev_b32_e32 v18, 8, v35
	v_cvt_u32_f32_sdwa v16, v16 dst_sel:BYTE_3 dst_unused:UNUSED_PAD src0_sel:DWORD
	v_cvt_u32_f32_sdwa v17, v17 dst_sel:BYTE_3 dst_unused:UNUSED_PAD src0_sel:DWORD
	v_lshlrev_b32_e32 v19, 8, v34
	v_or_b32_e32 v18, v18, v23
	v_or_b32_e32 v19, v19, v22
	v_or_b32_e32 v18, v18, v21
	v_or_b32_e32 v19, v19, v20
	v_or_b32_e32 v17, v18, v17
	v_or_b32_e32 v16, v19, v16
	v_mov_b64_e32 v[244:245], v[16:17]
	v_add_u32_e32 v16, 0xb0, v166
	v_ashrrev_i32_e32 v17, 31, v16
	v_lshlrev_b64 v[18:19], 6, v[16:17]
	v_lshl_add_u64 v[22:23], s[26:27], 0, v[18:19]
	s_mov_b64 s[26:27], -1
	s_cmp_eq_u32 s12, 2
	s_nop 0
	s_nop 0
	s_nop 0
	s_nop 0
	v_mov_b32_e32 v17, v235
	v_fma_f32 v8, v8, v17, v40
	v_mul_f32_e32 v8, 0xbfb8aa3b, v8
	v_fma_f32 v12, v12, v17, v44
	v_exp_f32_e32 v8, v8
	v_mul_f32_e32 v12, 0xbfb8aa3b, v12
	v_exp_f32_e32 v12, v12
	v_fma_f32 v10, v10, v17, v42
	v_mul_f32_e32 v10, 0xbfb8aa3b, v10
	v_add_f32_e32 v8, 1.0, v8
	v_exp_f32_e32 v10, v10
	v_rcp_f32_e32 v19, v8
	v_fma_f32 v8, v13, v17, v45
	v_fma_f32 v9, v9, v17, v41
	v_add_f32_e32 v12, 1.0, v12
	v_mul_f32_e32 v8, 0xbfb8aa3b, v8
	v_mul_f32_e32 v9, 0xbfb8aa3b, v9
	v_rcp_f32_e32 v18, v12
	v_exp_f32_e32 v8, v8
	v_exp_f32_e32 v9, v9
	v_fma_f32 v12, v14, v17, v46
	v_mul_f32_e32 v12, 0xbfb8aa3b, v12
	v_add_f32_e32 v10, 1.0, v10
	v_fmac_f32_e32 v47, v15, v17
	v_fmac_f32_e32 v43, v11, v17
	v_exp_f32_e32 v12, v12
	v_rcp_f32_e32 v13, v10
	v_mul_f32_e32 v10, 0xbfb8aa3b, v47
	v_mul_f32_e32 v11, 0xbfb8aa3b, v43
	v_exp_f32_e32 v10, v10
	v_exp_f32_e32 v11, v11
	v_add_f32_e32 v8, 1.0, v8
	v_add_f32_e32 v9, 1.0, v9
	v_rcp_f32_e32 v8, v8
	v_rcp_f32_e32 v9, v9
	v_add_f32_e32 v12, 1.0, v12
	v_rcp_f32_e32 v12, v12
	v_add_f32_e32 v10, 1.0, v10
	v_add_f32_e32 v11, 1.0, v11
	v_rcp_f32_e32 v10, v10
	v_rcp_f32_e32 v11, v11
	v_pk_fma_f32 v[8:9], v[8:9], s[36:37], 0.5 op_sel_hi:[1,0,0]
	v_pk_fma_f32 v[14:15], v[18:19], s[36:37], 0.5 op_sel_hi:[1,0,0]
	v_cvt_u32_f32_e32 v18, v8
	v_cvt_u32_f32_e32 v19, v9
	v_cvt_u32_f32_e32 v15, v15
	v_cvt_u32_f32_e32 v14, v14
	v_pk_fma_f32 v[8:9], v[12:13], s[36:37], 0.5 op_sel_hi:[1,0,0]
	v_fma_f32 v0, v0, v17, v24
	v_cvt_u32_f32_sdwa v12, v8 dst_sel:WORD_1 dst_unused:UNUSED_PAD src0_sel:DWORD
	v_cvt_u32_f32_sdwa v13, v9 dst_sel:WORD_1 dst_unused:UNUSED_PAD src0_sel:DWORD
	v_pk_fma_f32 v[8:9], v[10:11], s[36:37], 0.5 op_sel_hi:[1,0,0]
	v_mul_f32_e32 v0, 0xbfb8aa3b, v0
	v_cvt_u32_f32_sdwa v8, v8 dst_sel:BYTE_3 dst_unused:UNUSED_PAD src0_sel:DWORD
	v_cvt_u32_f32_sdwa v9, v9 dst_sel:BYTE_3 dst_unused:UNUSED_PAD src0_sel:DWORD
	v_lshlrev_b32_e32 v10, 8, v19
	v_lshlrev_b32_e32 v11, 8, v18
	v_fma_f32 v4, v4, v17, v28
	v_exp_f32_e32 v0, v0
	v_or_b32_e32 v10, v10, v15
	v_or_b32_e32 v11, v11, v14
	v_mul_f32_e32 v4, 0xbfb8aa3b, v4
	v_or_b32_e32 v10, v10, v13
	v_or_b32_e32 v12, v11, v12
	v_exp_f32_e32 v4, v4
	v_fma_f32 v2, v2, v17, v26
	v_or_b32_e32 v11, v10, v9
	v_or_b32_e32 v10, v12, v8
	v_mad_i64_i32 v[8:9], s[18:19], v16, s28, v[136:137]
	v_mul_f32_e32 v2, 0xbfb8aa3b, v2
	v_lshl_add_u64 v[8:9], v[8:9], 0, v[164:165]
	v_add_f32_e32 v0, 1.0, v0
	v_exp_f32_e32 v2, v2
	v_mov_b64_e32 v[242:243], v[10:11]
	s_nop 1
	v_permlane16_swap_b32_e32 v240, v242
	v_permlane16_swap_b32_e32 v241, v243
	global_store_dwordx4 v[248:249], v[240:243], off
	v_rcp_f32_e32 v11, v0
	v_fma_f32 v0, v5, v17, v29
	v_fma_f32 v1, v1, v17, v25
	v_add_f32_e32 v4, 1.0, v4
	v_mul_f32_e32 v0, 0xbfb8aa3b, v0
	v_mul_f32_e32 v1, 0xbfb8aa3b, v1
	v_rcp_f32_e32 v10, v4
	v_exp_f32_e32 v0, v0
	v_exp_f32_e32 v1, v1
	v_fma_f32 v4, v6, v17, v30
	v_mul_f32_e32 v4, 0xbfb8aa3b, v4
	v_add_f32_e32 v2, 1.0, v2
	v_fmac_f32_e32 v31, v7, v17
	v_fmac_f32_e32 v27, v3, v17
	v_exp_f32_e32 v4, v4
	v_rcp_f32_e32 v5, v2
	v_mul_f32_e32 v2, 0xbfb8aa3b, v31
	v_mul_f32_e32 v3, 0xbfb8aa3b, v27
	v_exp_f32_e32 v2, v2
	v_exp_f32_e32 v3, v3
	v_add_f32_e32 v0, 1.0, v0
	v_add_f32_e32 v1, 1.0, v1
	v_rcp_f32_e32 v0, v0
	v_rcp_f32_e32 v1, v1
	v_add_f32_e32 v4, 1.0, v4
	v_rcp_f32_e32 v4, v4
	v_add_f32_e32 v2, 1.0, v2
	v_add_f32_e32 v3, 1.0, v3
	v_rcp_f32_e32 v2, v2
	v_rcp_f32_e32 v3, v3
	v_pk_fma_f32 v[0:1], v[0:1], s[36:37], 0.5 op_sel_hi:[1,0,0]
	v_pk_fma_f32 v[6:7], v[10:11], s[36:37], 0.5 op_sel_hi:[1,0,0]
	v_cvt_u32_f32_e32 v10, v0
	v_cvt_u32_f32_e32 v11, v1
	v_cvt_u32_f32_e32 v7, v7
	v_cvt_u32_f32_e32 v6, v6
	v_pk_fma_f32 v[0:1], v[4:5], s[36:37], 0.5 op_sel_hi:[1,0,0]
	s_nop 0
	v_cvt_u32_f32_sdwa v4, v0 dst_sel:WORD_1 dst_unused:UNUSED_PAD src0_sel:DWORD
	v_cvt_u32_f32_sdwa v5, v1 dst_sel:WORD_1 dst_unused:UNUSED_PAD src0_sel:DWORD
	v_pk_fma_f32 v[0:1], v[2:3], s[36:37], 0.5 op_sel_hi:[1,0,0]
	v_lshlrev_b32_e32 v2, 8, v11
	v_cvt_u32_f32_sdwa v0, v0 dst_sel:BYTE_3 dst_unused:UNUSED_PAD src0_sel:DWORD
	v_cvt_u32_f32_sdwa v1, v1 dst_sel:BYTE_3 dst_unused:UNUSED_PAD src0_sel:DWORD
	v_lshlrev_b32_e32 v3, 8, v10
	v_or_b32_e32 v2, v2, v7
	v_or_b32_e32 v3, v3, v6
	v_or_b32_e32 v2, v2, v5
	v_or_b32_e32 v3, v3, v4
	v_or_b32_e32 v1, v2, v1
	v_or_b32_e32 v0, v3, v0
	v_mov_b64_e32 v[246:247], v[0:1]
	s_nop 1
	v_permlane16_swap_b32_e32 v244, v246
	v_permlane16_swap_b32_e32 v245, v247
	global_store_dwordx4 v[248:249], v[244:247], off offset:128
	s_cbranch_scc1 .LBB0_1565
	v_readlane_b32 s18, v254, 58
	v_readlane_b32 s19, v254, 59
	s_andn2_b64 vcc, exec, s[18:19]
	s_cbranch_vccnz .LBB0_1564
	s_barrier
	s_branch .LBB0_1564
